# RWKV scan: the six LDS reads of a step issued at the top of the step (more latency slack when the CU is shared)
# speedup vs baseline: 1.3767x; 1.0244x over previous
.Lscan_chunk:
	ds_read_b128 v[96:99], v139 offset:3456
	ds_read_b32 v104, v140 offset:2688
	ds_read_b128 v[88:91], v139 offset:2944
	ds_read_b128 v[84:87], v139 offset:2688
	ds_read_b128 v[92:95], v139 offset:3200
	ds_read_b128 v[100:103], v139 offset:3712
	v_pk_mul_f32 v[16:17], v[0:1], v[44:45]
	v_pk_mul_f32 v[20:21], v[0:1], v[122:123]
	v_pk_fma_f32 v[16:17], v[2:3], v[46:47], v[16:17]
	v_pk_fma_f32 v[20:21], v[2:3], v[124:125], v[20:21]
	v_add_f32_e32 v18, v16, v17
	v_pk_fma_f32 v[4:5], v[0:1], v[40:41], v[8:9]
	v_add_f32_e32 v201, v20, v21
	v_add_f32_dpp v18, v18, v18 quad_perm:[1,0,3,2] row_mask:0xf bank_mask:0xf bound_ctrl:1
	v_pk_fma_f32 v[6:7], v[2:3], v[42:43], v[10:11]
	s_nop 0
	v_add_f32_dpp v18, v18, v18 quad_perm:[2,3,0,1] row_mask:0xf bank_mask:0xf bound_ctrl:1
	v_add_f32_dpp v201, v201, v201 row_ror:8 row_mask:0xf bank_mask:0xc bound_ctrl:1
	v_add_f32_dpp v18, v18, v18 row_half_mirror row_mask:0xf bank_mask:0xf bound_ctrl:1
	v_add_f32_dpp v201, v191, v191 row_ror:8 row_mask:0xf bank_mask:0x3 bound_ctrl:1
	v_add_f32_dpp v18, v18, v18 row_ror:8 row_mask:0xf bank_mask:0xf bound_ctrl:1
	v_pk_fma_f32 v[0:1], v[48:49], v[18:19], v[4:5] op_sel_hi:[1,0,1] neg_lo:[1,0,0] neg_hi:[1,0,0]
	v_pk_fma_f32 v[2:3], v[50:51], v[18:19], v[6:7] op_sel_hi:[1,0,1] neg_lo:[1,0,0] neg_hi:[1,0,0]
	s_waitcnt lgkmcnt(6)
	v_pk_mul_f32 v[8:9], v[74:75], v[82:83] op_sel_hi:[1,0]
	v_pk_mul_f32 v[10:11], v[76:77], v[82:83] op_sel_hi:[1,0]
	ds_read_b128 v[118:121], v139 offset:4800
	ds_read_b32 v126, v140 offset:4032
	ds_read_b128 v[110:113], v139 offset:4288
	ds_read_b128 v[106:109], v139 offset:4032
	ds_read_b128 v[114:117], v139 offset:4544
	ds_read_b128 v[122:125], v139 offset:5056
	v_pk_mul_f32 v[16:17], v[0:1], v[66:67]
	v_pk_mul_f32 v[20:21], v[0:1], v[56:57]
	v_pk_fma_f32 v[16:17], v[2:3], v[68:69], v[16:17]
	v_pk_fma_f32 v[20:21], v[2:3], v[58:59], v[20:21]
	v_add_f32_e32 v18, v16, v17
	v_pk_fma_f32 v[4:5], v[0:1], v[62:63], v[8:9]
	v_add_f32_e32 v12, v20, v21
	v_add_f32_dpp v18, v18, v18 quad_perm:[1,0,3,2] row_mask:0xf bank_mask:0xf bound_ctrl:1
	v_pk_fma_f32 v[6:7], v[2:3], v[64:65], v[10:11]
	v_add_f32_dpp v196, v196, v196 row_half_mirror row_mask:0xf bank_mask:0xa bound_ctrl:1
	v_add_f32_dpp v18, v18, v18 quad_perm:[2,3,0,1] row_mask:0xf bank_mask:0xf bound_ctrl:1
	v_add_f32_dpp v196, v192, v192 row_half_mirror row_mask:0xf bank_mask:0x5 bound_ctrl:1
	v_add_f32_dpp v18, v18, v18 row_half_mirror row_mask:0xf bank_mask:0xf bound_ctrl:1
	v_add_f32_dpp v197, v197, v197 row_half_mirror row_mask:0xf bank_mask:0xa bound_ctrl:1
	v_add_f32_dpp v18, v18, v18 row_ror:8 row_mask:0xf bank_mask:0xf bound_ctrl:1
	v_pk_fma_f32 v[0:1], v[70:71], v[18:19], v[4:5] op_sel_hi:[1,0,1] neg_lo:[1,0,0] neg_hi:[1,0,0]
	v_pk_fma_f32 v[2:3], v[72:73], v[18:19], v[6:7] op_sel_hi:[1,0,1] neg_lo:[1,0,0] neg_hi:[1,0,0]
	s_waitcnt lgkmcnt(6)
	v_pk_mul_f32 v[8:9], v[96:97], v[104:105] op_sel_hi:[1,0]
	v_pk_mul_f32 v[10:11], v[98:99], v[104:105] op_sel_hi:[1,0]
	ds_read_b128 v[52:55], v139 offset:6144
	ds_read_b32 v60, v140 offset:5376
	ds_read_b128 v[44:47], v139 offset:5632
	ds_read_b128 v[40:43], v139 offset:5376
	ds_read_b128 v[48:51], v139 offset:5888
	ds_read_b128 v[56:59], v139 offset:6400
	v_pk_mul_f32 v[16:17], v[0:1], v[88:89]
	v_pk_mul_f32 v[20:21], v[0:1], v[78:79]
	v_pk_fma_f32 v[16:17], v[2:3], v[90:91], v[16:17]
	v_pk_fma_f32 v[20:21], v[2:3], v[80:81], v[20:21]
	v_add_f32_e32 v18, v16, v17
	v_pk_fma_f32 v[4:5], v[0:1], v[84:85], v[8:9]
	v_add_f32_e32 v13, v20, v21
	v_add_f32_dpp v18, v18, v18 quad_perm:[1,0,3,2] row_mask:0xf bank_mask:0xf bound_ctrl:1
	v_pk_fma_f32 v[6:7], v[2:3], v[86:87], v[10:11]
	v_add_f32_dpp v197, v193, v193 row_half_mirror row_mask:0xf bank_mask:0x5 bound_ctrl:1
	v_add_f32_dpp v18, v18, v18 quad_perm:[2,3,0,1] row_mask:0xf bank_mask:0xf bound_ctrl:1
	v_add_f32_dpp v200, v200, v200 row_half_mirror row_mask:0xf bank_mask:0xa bound_ctrl:1
	v_add_f32_dpp v18, v18, v18 row_half_mirror row_mask:0xf bank_mask:0xf bound_ctrl:1
	v_add_f32_dpp v200, v194, v194 row_half_mirror row_mask:0xf bank_mask:0x5 bound_ctrl:1
	v_add_f32_dpp v18, v18, v18 row_ror:8 row_mask:0xf bank_mask:0xf bound_ctrl:1
	v_pk_fma_f32 v[0:1], v[92:93], v[18:19], v[4:5] op_sel_hi:[1,0,1] neg_lo:[1,0,0] neg_hi:[1,0,0]
	v_pk_fma_f32 v[2:3], v[94:95], v[18:19], v[6:7] op_sel_hi:[1,0,1] neg_lo:[1,0,0] neg_hi:[1,0,0]
	s_waitcnt lgkmcnt(6)
	v_pk_mul_f32 v[8:9], v[118:119], v[126:127] op_sel_hi:[1,0]
	v_pk_mul_f32 v[10:11], v[120:121], v[126:127] op_sel_hi:[1,0]
	ds_read_b128 v[74:77], v139 offset:7488
	ds_read_b32 v82, v140 offset:6720
	ds_read_b128 v[66:69], v139 offset:6976
	ds_read_b128 v[62:65], v139 offset:6720
	ds_read_b128 v[70:73], v139 offset:7232
	ds_read_b128 v[78:81], v139 offset:7744
	v_pk_mul_f32 v[16:17], v[0:1], v[110:111]
	v_pk_mul_f32 v[20:21], v[0:1], v[100:101]
	v_pk_fma_f32 v[16:17], v[2:3], v[112:113], v[16:17]
	v_pk_fma_f32 v[20:21], v[2:3], v[102:103], v[20:21]
	v_add_f32_e32 v18, v16, v17
	v_pk_fma_f32 v[4:5], v[0:1], v[106:107], v[8:9]
	v_add_f32_e32 v14, v20, v21
	v_add_f32_dpp v18, v18, v18 quad_perm:[1,0,3,2] row_mask:0xf bank_mask:0xf bound_ctrl:1
	v_pk_fma_f32 v[6:7], v[2:3], v[108:109], v[10:11]
	v_add_f32_dpp v201, v201, v201 row_half_mirror row_mask:0xf bank_mask:0xa bound_ctrl:1
	v_add_f32_dpp v18, v18, v18 quad_perm:[2,3,0,1] row_mask:0xf bank_mask:0xf bound_ctrl:1
	v_add_f32_dpp v201, v195, v195 row_half_mirror row_mask:0xf bank_mask:0x5 bound_ctrl:1
	v_add_f32_dpp v18, v18, v18 row_half_mirror row_mask:0xf bank_mask:0xf bound_ctrl:1
	v_cndmask_b32_e64 v22, v196, v200, s[36:37]
	v_add_f32_dpp v18, v18, v18 row_ror:8 row_mask:0xf bank_mask:0xf bound_ctrl:1
	v_pk_fma_f32 v[0:1], v[114:115], v[18:19], v[4:5] op_sel_hi:[1,0,1] neg_lo:[1,0,0] neg_hi:[1,0,0]
	v_pk_fma_f32 v[2:3], v[116:117], v[18:19], v[6:7] op_sel_hi:[1,0,1] neg_lo:[1,0,0] neg_hi:[1,0,0]
	s_waitcnt lgkmcnt(6)
	v_pk_mul_f32 v[8:9], v[52:53], v[60:61] op_sel_hi:[1,0]
	v_pk_mul_f32 v[10:11], v[54:55], v[60:61] op_sel_hi:[1,0]
	ds_read_b128 v[96:99], v139 offset:8832
	ds_read_b32 v104, v140 offset:8064
	ds_read_b128 v[88:91], v139 offset:8320
	ds_read_b128 v[84:87], v139 offset:8064
	ds_read_b128 v[92:95], v139 offset:8576
	ds_read_b128 v[100:103], v139 offset:9088
	v_pk_mul_f32 v[16:17], v[0:1], v[44:45]
	v_pk_mul_f32 v[20:21], v[0:1], v[122:123]
	v_pk_fma_f32 v[16:17], v[2:3], v[46:47], v[16:17]
	v_pk_fma_f32 v[20:21], v[2:3], v[124:125], v[20:21]
	v_add_f32_e32 v18, v16, v17
	v_pk_fma_f32 v[4:5], v[0:1], v[40:41], v[8:9]
	v_add_f32_e32 v15, v20, v21
	v_add_f32_dpp v18, v18, v18 quad_perm:[1,0,3,2] row_mask:0xf bank_mask:0xf bound_ctrl:1
	v_pk_fma_f32 v[6:7], v[2:3], v[42:43], v[10:11]
	v_cndmask_b32_e64 v202, v200, v196, s[36:37]
	v_add_f32_dpp v18, v18, v18 quad_perm:[2,3,0,1] row_mask:0xf bank_mask:0xf bound_ctrl:1
	v_add_f32_dpp v200, v202, v22 quad_perm:[2,3,0,1] row_mask:0xf bank_mask:0xf bound_ctrl:1
	v_add_f32_dpp v18, v18, v18 row_half_mirror row_mask:0xf bank_mask:0xf bound_ctrl:1
	v_cndmask_b32_e64 v203, v197, v201, s[36:37]
	v_add_f32_dpp v18, v18, v18 row_ror:8 row_mask:0xf bank_mask:0xf bound_ctrl:1
	v_pk_fma_f32 v[0:1], v[48:49], v[18:19], v[4:5] op_sel_hi:[1,0,1] neg_lo:[1,0,0] neg_hi:[1,0,0]
	v_pk_fma_f32 v[2:3], v[50:51], v[18:19], v[6:7] op_sel_hi:[1,0,1] neg_lo:[1,0,0] neg_hi:[1,0,0]
	s_waitcnt lgkmcnt(6)
	v_pk_mul_f32 v[8:9], v[74:75], v[82:83] op_sel_hi:[1,0]
	v_pk_mul_f32 v[10:11], v[76:77], v[82:83] op_sel_hi:[1,0]
	ds_read_b128 v[118:121], v139 offset:10176
	ds_read_b32 v126, v140 offset:9408
	ds_read_b128 v[110:113], v139 offset:9664
	ds_read_b128 v[106:109], v139 offset:9408
	ds_read_b128 v[114:117], v139 offset:9920
	ds_read_b128 v[122:125], v139 offset:10432
	v_pk_mul_f32 v[16:17], v[0:1], v[66:67]
	v_pk_mul_f32 v[20:21], v[0:1], v[56:57]
	v_pk_fma_f32 v[16:17], v[2:3], v[68:69], v[16:17]
	v_pk_fma_f32 v[20:21], v[2:3], v[58:59], v[20:21]
	v_add_f32_e32 v18, v16, v17
	v_pk_fma_f32 v[4:5], v[0:1], v[62:63], v[8:9]
	v_add_f32_e32 v188, v20, v21
	v_add_f32_dpp v18, v18, v18 quad_perm:[1,0,3,2] row_mask:0xf bank_mask:0xf bound_ctrl:1
	v_pk_fma_f32 v[6:7], v[2:3], v[64:65], v[10:11]
	v_cndmask_b32_e64 v202, v201, v197, s[36:37]
	v_add_f32_dpp v18, v18, v18 quad_perm:[2,3,0,1] row_mask:0xf bank_mask:0xf bound_ctrl:1
	v_add_f32_dpp v201, v202, v203 quad_perm:[2,3,0,1] row_mask:0xf bank_mask:0xf bound_ctrl:1
	v_add_f32_dpp v18, v18, v18 row_half_mirror row_mask:0xf bank_mask:0xf bound_ctrl:1
	v_cndmask_b32_e64 v22, v200, v201, s[38:39]
	v_add_f32_dpp v18, v18, v18 row_ror:8 row_mask:0xf bank_mask:0xf bound_ctrl:1
	v_pk_fma_f32 v[0:1], v[70:71], v[18:19], v[4:5] op_sel_hi:[1,0,1] neg_lo:[1,0,0] neg_hi:[1,0,0]
	v_pk_fma_f32 v[2:3], v[72:73], v[18:19], v[6:7] op_sel_hi:[1,0,1] neg_lo:[1,0,0] neg_hi:[1,0,0]
	s_waitcnt lgkmcnt(6)
	v_pk_mul_f32 v[8:9], v[96:97], v[104:105] op_sel_hi:[1,0]
	v_pk_mul_f32 v[10:11], v[98:99], v[104:105] op_sel_hi:[1,0]
	ds_read_b128 v[52:55], v139 offset:11520
	ds_read_b32 v60, v140 offset:10752
	ds_read_b128 v[44:47], v139 offset:11008
	ds_read_b128 v[40:43], v139 offset:10752
	ds_read_b128 v[48:51], v139 offset:11264
	ds_read_b128 v[56:59], v139 offset:11776
	v_pk_mul_f32 v[16:17], v[0:1], v[88:89]
	v_pk_mul_f32 v[20:21], v[0:1], v[78:79]
	v_pk_fma_f32 v[16:17], v[2:3], v[90:91], v[16:17]
	v_pk_fma_f32 v[20:21], v[2:3], v[80:81], v[20:21]
	v_add_f32_e32 v18, v16, v17
	v_pk_fma_f32 v[4:5], v[0:1], v[84:85], v[8:9]
	v_add_f32_e32 v189, v20, v21
	v_add_f32_dpp v18, v18, v18 quad_perm:[1,0,3,2] row_mask:0xf bank_mask:0xf bound_ctrl:1
	v_pk_fma_f32 v[6:7], v[2:3], v[86:87], v[10:11]
	v_cndmask_b32_e64 v202, v201, v200, s[38:39]
	v_add_f32_dpp v18, v18, v18 quad_perm:[2,3,0,1] row_mask:0xf bank_mask:0xf bound_ctrl:1
	v_add_f32_dpp v23, v202, v22 quad_perm:[1,0,3,2] row_mask:0xf bank_mask:0xf bound_ctrl:1
	v_add_f32_dpp v18, v18, v18 row_half_mirror row_mask:0xf bank_mask:0xf bound_ctrl:1
	s_nop 0
	v_add_f32_dpp v18, v18, v18 row_ror:8 row_mask:0xf bank_mask:0xf bound_ctrl:1
	v_pk_fma_f32 v[0:1], v[92:93], v[18:19], v[4:5] op_sel_hi:[1,0,1] neg_lo:[1,0,0] neg_hi:[1,0,0]
	v_pk_fma_f32 v[2:3], v[94:95], v[18:19], v[6:7] op_sel_hi:[1,0,1] neg_lo:[1,0,0] neg_hi:[1,0,0]
	s_waitcnt lgkmcnt(6)
	v_pk_mul_f32 v[8:9], v[118:119], v[126:127] op_sel_hi:[1,0]
	v_pk_mul_f32 v[10:11], v[120:121], v[126:127] op_sel_hi:[1,0]
	s_cmp_eq_u32 s4, 0
	s_cbranch_scc1 .Lscan_noy0
	global_store_dword v138, v23, s[96:97]
	v_add_u32_e32 v138, s90, v138
.Lscan_noy0:
	ds_read_b128 v[74:77], v139 offset:12864
	ds_read_b32 v82, v140 offset:12096
	ds_read_b128 v[66:69], v139 offset:12352
	ds_read_b128 v[62:65], v139 offset:12096
	ds_read_b128 v[70:73], v139 offset:12608
	ds_read_b128 v[78:81], v139 offset:13120
	v_pk_mul_f32 v[16:17], v[0:1], v[110:111]
	v_pk_mul_f32 v[20:21], v[0:1], v[100:101]
	v_pk_fma_f32 v[16:17], v[2:3], v[112:113], v[16:17]
	v_pk_fma_f32 v[20:21], v[2:3], v[102:103], v[20:21]
	v_add_f32_e32 v18, v16, v17
	v_pk_fma_f32 v[4:5], v[0:1], v[106:107], v[8:9]
	v_add_f32_e32 v190, v20, v21
	v_add_f32_dpp v18, v18, v18 quad_perm:[1,0,3,2] row_mask:0xf bank_mask:0xf bound_ctrl:1
	v_pk_fma_f32 v[6:7], v[2:3], v[108:109], v[10:11]
	s_nop 0
	v_add_f32_dpp v18, v18, v18 quad_perm:[2,3,0,1] row_mask:0xf bank_mask:0xf bound_ctrl:1
	s_nop 0
	v_add_f32_dpp v18, v18, v18 row_half_mirror row_mask:0xf bank_mask:0xf bound_ctrl:1
	s_nop 0
	v_add_f32_dpp v18, v18, v18 row_ror:8 row_mask:0xf bank_mask:0xf bound_ctrl:1
	v_pk_fma_f32 v[0:1], v[114:115], v[18:19], v[4:5] op_sel_hi:[1,0,1] neg_lo:[1,0,0] neg_hi:[1,0,0]
	v_pk_fma_f32 v[2:3], v[116:117], v[18:19], v[6:7] op_sel_hi:[1,0,1] neg_lo:[1,0,0] neg_hi:[1,0,0]
	s_waitcnt lgkmcnt(6)
	v_pk_mul_f32 v[8:9], v[52:53], v[60:61] op_sel_hi:[1,0]
	v_pk_mul_f32 v[10:11], v[54:55], v[60:61] op_sel_hi:[1,0]
	ds_read_b128 v[96:99], v139 offset:14208
	ds_read_b32 v104, v140 offset:13440
	ds_read_b128 v[88:91], v139 offset:13696
	ds_read_b128 v[84:87], v139 offset:13440
	ds_read_b128 v[92:95], v139 offset:13952
	ds_read_b128 v[100:103], v139 offset:14464
	v_pk_mul_f32 v[16:17], v[0:1], v[44:45]
	v_pk_mul_f32 v[20:21], v[0:1], v[122:123]
	v_pk_fma_f32 v[16:17], v[2:3], v[46:47], v[16:17]
	v_pk_fma_f32 v[20:21], v[2:3], v[124:125], v[20:21]
	v_add_f32_e32 v18, v16, v17
	v_pk_fma_f32 v[4:5], v[0:1], v[40:41], v[8:9]
	v_add_f32_e32 v191, v20, v21
	v_add_f32_dpp v18, v18, v18 quad_perm:[1,0,3,2] row_mask:0xf bank_mask:0xf bound_ctrl:1
	v_pk_fma_f32 v[6:7], v[2:3], v[42:43], v[10:11]
	s_nop 0
	v_add_f32_dpp v18, v18, v18 quad_perm:[2,3,0,1] row_mask:0xf bank_mask:0xf bound_ctrl:1
	s_nop 0
	v_add_f32_dpp v18, v18, v18 row_half_mirror row_mask:0xf bank_mask:0xf bound_ctrl:1
	s_nop 0
	v_add_f32_dpp v18, v18, v18 row_ror:8 row_mask:0xf bank_mask:0xf bound_ctrl:1
	v_pk_fma_f32 v[0:1], v[48:49], v[18:19], v[4:5] op_sel_hi:[1,0,1] neg_lo:[1,0,0] neg_hi:[1,0,0]
	v_pk_fma_f32 v[2:3], v[50:51], v[18:19], v[6:7] op_sel_hi:[1,0,1] neg_lo:[1,0,0] neg_hi:[1,0,0]
	s_waitcnt lgkmcnt(6)
	v_pk_mul_f32 v[8:9], v[74:75], v[82:83] op_sel_hi:[1,0]
	v_pk_mul_f32 v[10:11], v[76:77], v[82:83] op_sel_hi:[1,0]
	ds_read_b128 v[118:121], v139 offset:15552
	ds_read_b32 v126, v140 offset:14784
	ds_read_b128 v[110:113], v139 offset:15040
	ds_read_b128 v[106:109], v139 offset:14784
	ds_read_b128 v[114:117], v139 offset:15296
	ds_read_b128 v[122:125], v139 offset:15808
	v_pk_mul_f32 v[16:17], v[0:1], v[66:67]
	v_pk_mul_f32 v[20:21], v[0:1], v[56:57]
	v_pk_fma_f32 v[16:17], v[2:3], v[68:69], v[16:17]
	v_pk_fma_f32 v[20:21], v[2:3], v[58:59], v[20:21]
	v_add_f32_e32 v18, v16, v17
	v_pk_fma_f32 v[4:5], v[0:1], v[62:63], v[8:9]
	v_add_f32_e32 v192, v20, v21
	v_add_f32_dpp v18, v18, v18 quad_perm:[1,0,3,2] row_mask:0xf bank_mask:0xf bound_ctrl:1
	v_pk_fma_f32 v[6:7], v[2:3], v[64:65], v[10:11]
	s_nop 0
	v_add_f32_dpp v18, v18, v18 quad_perm:[2,3,0,1] row_mask:0xf bank_mask:0xf bound_ctrl:1
	v_add_f32_dpp v192, v192, v192 row_ror:8 row_mask:0xf bank_mask:0xc bound_ctrl:1
	v_add_f32_dpp v18, v18, v18 row_half_mirror row_mask:0xf bank_mask:0xf bound_ctrl:1
	v_add_f32_dpp v192, v12, v12 row_ror:8 row_mask:0xf bank_mask:0x3 bound_ctrl:1
	v_add_f32_dpp v18, v18, v18 row_ror:8 row_mask:0xf bank_mask:0xf bound_ctrl:1
	v_pk_fma_f32 v[0:1], v[70:71], v[18:19], v[4:5] op_sel_hi:[1,0,1] neg_lo:[1,0,0] neg_hi:[1,0,0]
	v_pk_fma_f32 v[2:3], v[72:73], v[18:19], v[6:7] op_sel_hi:[1,0,1] neg_lo:[1,0,0] neg_hi:[1,0,0]
	s_waitcnt lgkmcnt(6)
	v_pk_mul_f32 v[8:9], v[96:97], v[104:105] op_sel_hi:[1,0]
	v_pk_mul_f32 v[10:11], v[98:99], v[104:105] op_sel_hi:[1,0]
	ds_read_b128 v[52:55], v139 offset:16896
	ds_read_b32 v60, v140 offset:16128
	ds_read_b128 v[44:47], v139 offset:16384
	ds_read_b128 v[40:43], v139 offset:16128
	ds_read_b128 v[48:51], v139 offset:16640
	ds_read_b128 v[56:59], v139 offset:17152
	v_pk_mul_f32 v[16:17], v[0:1], v[88:89]
	v_pk_mul_f32 v[20:21], v[0:1], v[78:79]
	v_pk_fma_f32 v[16:17], v[2:3], v[90:91], v[16:17]
	v_pk_fma_f32 v[20:21], v[2:3], v[80:81], v[20:21]
	v_add_f32_e32 v18, v16, v17
	v_pk_fma_f32 v[4:5], v[0:1], v[84:85], v[8:9]
	v_add_f32_e32 v193, v20, v21
	v_add_f32_dpp v18, v18, v18 quad_perm:[1,0,3,2] row_mask:0xf bank_mask:0xf bound_ctrl:1
	v_pk_fma_f32 v[6:7], v[2:3], v[86:87], v[10:11]
	s_nop 0
	v_add_f32_dpp v18, v18, v18 quad_perm:[2,3,0,1] row_mask:0xf bank_mask:0xf bound_ctrl:1
	v_add_f32_dpp v193, v193, v193 row_ror:8 row_mask:0xf bank_mask:0xc bound_ctrl:1
	v_add_f32_dpp v18, v18, v18 row_half_mirror row_mask:0xf bank_mask:0xf bound_ctrl:1
	v_add_f32_dpp v193, v13, v13 row_ror:8 row_mask:0xf bank_mask:0x3 bound_ctrl:1
	v_add_f32_dpp v18, v18, v18 row_ror:8 row_mask:0xf bank_mask:0xf bound_ctrl:1
	v_pk_fma_f32 v[0:1], v[92:93], v[18:19], v[4:5] op_sel_hi:[1,0,1] neg_lo:[1,0,0] neg_hi:[1,0,0]
	v_pk_fma_f32 v[2:3], v[94:95], v[18:19], v[6:7] op_sel_hi:[1,0,1] neg_lo:[1,0,0] neg_hi:[1,0,0]
	s_waitcnt lgkmcnt(6)
	v_pk_mul_f32 v[8:9], v[118:119], v[126:127] op_sel_hi:[1,0]
	v_pk_mul_f32 v[10:11], v[120:121], v[126:127] op_sel_hi:[1,0]
	s_add_i32 s0, s4, 2
	s_cmp_lt_u32 s0, s5
	s_cbranch_scc1 .Lscan_w6_0
	s_waitcnt vmcnt(0)
	s_branch .Lscan_wd_0

.Lscan_wd_0:
	ds_write_b128 v143, v[146:149]
	ds_write_b128 v143, v[150:153] offset:256
	ds_write_b128 v143, v[154:157] offset:512
	ds_write_b128 v143, v[158:161] offset:768
	ds_write_b128 v143, v[162:165] offset:1024
	ds_write_b32 v35, v166
	ds_read_b128 v[74:77], v139 offset:18240
	ds_read_b32 v82, v140 offset:17472
	ds_read_b128 v[66:69], v139 offset:17728
	ds_read_b128 v[62:65], v139 offset:17472
	ds_read_b128 v[70:73], v139 offset:17984
	ds_read_b128 v[78:81], v139 offset:18496
	v_pk_mul_f32 v[16:17], v[0:1], v[110:111]
	v_pk_mul_f32 v[20:21], v[0:1], v[100:101]
	v_pk_fma_f32 v[16:17], v[2:3], v[112:113], v[16:17]
	v_pk_fma_f32 v[20:21], v[2:3], v[102:103], v[20:21]
	v_add_f32_e32 v18, v16, v17
	v_pk_fma_f32 v[4:5], v[0:1], v[106:107], v[8:9]
	v_add_f32_e32 v194, v20, v21
	v_add_f32_dpp v18, v18, v18 quad_perm:[1,0,3,2] row_mask:0xf bank_mask:0xf bound_ctrl:1
	v_pk_fma_f32 v[6:7], v[2:3], v[108:109], v[10:11]
	s_nop 0
	v_add_f32_dpp v18, v18, v18 quad_perm:[2,3,0,1] row_mask:0xf bank_mask:0xf bound_ctrl:1
	v_add_f32_dpp v194, v194, v194 row_ror:8 row_mask:0xf bank_mask:0xc bound_ctrl:1
	v_add_f32_dpp v18, v18, v18 row_half_mirror row_mask:0xf bank_mask:0xf bound_ctrl:1
	v_add_f32_dpp v194, v14, v14 row_ror:8 row_mask:0xf bank_mask:0x3 bound_ctrl:1
	v_add_f32_dpp v18, v18, v18 row_ror:8 row_mask:0xf bank_mask:0xf bound_ctrl:1
	v_pk_fma_f32 v[0:1], v[114:115], v[18:19], v[4:5] op_sel_hi:[1,0,1] neg_lo:[1,0,0] neg_hi:[1,0,0]
	v_pk_fma_f32 v[2:3], v[116:117], v[18:19], v[6:7] op_sel_hi:[1,0,1] neg_lo:[1,0,0] neg_hi:[1,0,0]
	s_waitcnt lgkmcnt(6)
	v_pk_mul_f32 v[8:9], v[52:53], v[60:61] op_sel_hi:[1,0]
	v_pk_mul_f32 v[10:11], v[54:55], v[60:61] op_sel_hi:[1,0]
	ds_read_b128 v[96:99], v139 offset:19584
	ds_read_b32 v104, v140 offset:18816
	ds_read_b128 v[88:91], v139 offset:19072
	ds_read_b128 v[84:87], v139 offset:18816
	ds_read_b128 v[92:95], v139 offset:19328
	ds_read_b128 v[100:103], v139 offset:19840
	v_pk_mul_f32 v[16:17], v[0:1], v[44:45]
	v_pk_mul_f32 v[20:21], v[0:1], v[122:123]
	v_pk_fma_f32 v[16:17], v[2:3], v[46:47], v[16:17]
	v_pk_fma_f32 v[20:21], v[2:3], v[124:125], v[20:21]
	v_add_f32_e32 v18, v16, v17
	v_pk_fma_f32 v[4:5], v[0:1], v[40:41], v[8:9]
	v_add_f32_e32 v195, v20, v21
	v_add_f32_dpp v18, v18, v18 quad_perm:[1,0,3,2] row_mask:0xf bank_mask:0xf bound_ctrl:1
	v_pk_fma_f32 v[6:7], v[2:3], v[42:43], v[10:11]
	s_nop 0
	v_add_f32_dpp v18, v18, v18 quad_perm:[2,3,0,1] row_mask:0xf bank_mask:0xf bound_ctrl:1
	v_add_f32_dpp v195, v195, v195 row_ror:8 row_mask:0xf bank_mask:0xc bound_ctrl:1
	v_add_f32_dpp v18, v18, v18 row_half_mirror row_mask:0xf bank_mask:0xf bound_ctrl:1
	v_add_f32_dpp v195, v15, v15 row_ror:8 row_mask:0xf bank_mask:0x3 bound_ctrl:1
	v_add_f32_dpp v18, v18, v18 row_ror:8 row_mask:0xf bank_mask:0xf bound_ctrl:1
	v_pk_fma_f32 v[0:1], v[48:49], v[18:19], v[4:5] op_sel_hi:[1,0,1] neg_lo:[1,0,0] neg_hi:[1,0,0]
	v_pk_fma_f32 v[2:3], v[50:51], v[18:19], v[6:7] op_sel_hi:[1,0,1] neg_lo:[1,0,0] neg_hi:[1,0,0]
	s_waitcnt lgkmcnt(6)
	s_barrier
	s_add_i32 s0, s4, 3
	s_cmp_lt_u32 s0, s5
	s_cbranch_scc0 .Lscan_nold0
	s_mul_i32 s92, s0, s90
	v_add_u32_e32 v132, s92, v28
	v_add_u32_e32 v133, s92, v29
	v_add_u32_e32 v134, s92, v30
	v_add_u32_e32 v135, s92, v31
	v_add_u32_e32 v136, s92, v32
	v_add_u32_e32 v137, s92, v33
	global_load_dwordx4 v[146:149], v132, s[96:97]
	global_load_dwordx4 v[150:153], v133, s[96:97]
	global_load_dwordx4 v[154:157], v134, s[96:97]
	global_load_dwordx4 v[158:161], v135, s[96:97]
	global_load_dwordx4 v[162:165], v136, s[96:97]
	global_load_dword v166, v137, s[96:97]
.Lscan_nold0:
	v_pk_mul_f32 v[8:9], v[74:75], v[82:83] op_sel_hi:[1,0]
	v_pk_mul_f32 v[10:11], v[76:77], v[82:83] op_sel_hi:[1,0]
	ds_read_b128 v[118:121], v139 offset:20928
	ds_read_b32 v126, v140 offset:20160
	ds_read_b128 v[110:113], v139 offset:20416
	ds_read_b128 v[106:109], v139 offset:20160
	ds_read_b128 v[114:117], v139 offset:20672
	ds_read_b128 v[122:125], v139 offset:21184
	v_pk_mul_f32 v[16:17], v[0:1], v[66:67]
	v_pk_mul_f32 v[20:21], v[0:1], v[56:57]
	v_pk_fma_f32 v[16:17], v[2:3], v[68:69], v[16:17]
	v_pk_fma_f32 v[20:21], v[2:3], v[58:59], v[20:21]
	v_add_f32_e32 v18, v16, v17
	v_pk_fma_f32 v[4:5], v[0:1], v[62:63], v[8:9]
	v_add_f32_e32 v196, v20, v21
	v_add_f32_dpp v18, v18, v18 quad_perm:[1,0,3,2] row_mask:0xf bank_mask:0xf bound_ctrl:1
	v_pk_fma_f32 v[6:7], v[2:3], v[64:65], v[10:11]
	s_nop 0
	v_add_f32_dpp v18, v18, v18 quad_perm:[2,3,0,1] row_mask:0xf bank_mask:0xf bound_ctrl:1
	v_add_f32_dpp v196, v196, v196 row_ror:8 row_mask:0xf bank_mask:0xc bound_ctrl:1
	v_add_f32_dpp v18, v18, v18 row_half_mirror row_mask:0xf bank_mask:0xf bound_ctrl:1
	v_add_f32_dpp v196, v188, v188 row_ror:8 row_mask:0xf bank_mask:0x3 bound_ctrl:1
	v_add_f32_dpp v18, v18, v18 row_ror:8 row_mask:0xf bank_mask:0xf bound_ctrl:1
	v_pk_fma_f32 v[0:1], v[70:71], v[18:19], v[4:5] op_sel_hi:[1,0,1] neg_lo:[1,0,0] neg_hi:[1,0,0]
	v_pk_fma_f32 v[2:3], v[72:73], v[18:19], v[6:7] op_sel_hi:[1,0,1] neg_lo:[1,0,0] neg_hi:[1,0,0]
	s_waitcnt lgkmcnt(6)
	v_pk_mul_f32 v[8:9], v[96:97], v[104:105] op_sel_hi:[1,0]
	v_pk_mul_f32 v[10:11], v[98:99], v[104:105] op_sel_hi:[1,0]
	ds_read_b128 v[52:55], v141 offset:768
	ds_read_b32 v60, v142 offset:0
	ds_read_b128 v[44:47], v141 offset:256
	ds_read_b128 v[40:43], v141 offset:0
	ds_read_b128 v[48:51], v141 offset:512
	ds_read_b128 v[56:59], v141 offset:1024
	v_pk_mul_f32 v[16:17], v[0:1], v[88:89]
	v_pk_mul_f32 v[20:21], v[0:1], v[78:79]
	v_pk_fma_f32 v[16:17], v[2:3], v[90:91], v[16:17]
	v_pk_fma_f32 v[20:21], v[2:3], v[80:81], v[20:21]
	v_add_f32_e32 v18, v16, v17
	v_pk_fma_f32 v[4:5], v[0:1], v[84:85], v[8:9]
	v_add_f32_e32 v197, v20, v21
	v_add_f32_dpp v18, v18, v18 quad_perm:[1,0,3,2] row_mask:0xf bank_mask:0xf bound_ctrl:1
	v_pk_fma_f32 v[6:7], v[2:3], v[86:87], v[10:11]
	s_nop 0
	v_add_f32_dpp v18, v18, v18 quad_perm:[2,3,0,1] row_mask:0xf bank_mask:0xf bound_ctrl:1
	v_add_f32_dpp v197, v197, v197 row_ror:8 row_mask:0xf bank_mask:0xc bound_ctrl:1
	v_add_f32_dpp v18, v18, v18 row_half_mirror row_mask:0xf bank_mask:0xf bound_ctrl:1
	v_add_f32_dpp v197, v189, v189 row_ror:8 row_mask:0xf bank_mask:0x3 bound_ctrl:1
	v_add_f32_dpp v18, v18, v18 row_ror:8 row_mask:0xf bank_mask:0xf bound_ctrl:1
	v_pk_fma_f32 v[0:1], v[92:93], v[18:19], v[4:5] op_sel_hi:[1,0,1] neg_lo:[1,0,0] neg_hi:[1,0,0]
	v_pk_fma_f32 v[2:3], v[94:95], v[18:19], v[6:7] op_sel_hi:[1,0,1] neg_lo:[1,0,0] neg_hi:[1,0,0]
	s_waitcnt lgkmcnt(6)
	v_pk_mul_f32 v[8:9], v[118:119], v[126:127] op_sel_hi:[1,0]
	v_pk_mul_f32 v[10:11], v[120:121], v[126:127] op_sel_hi:[1,0]
	ds_read_b128 v[74:77], v141 offset:2112
	ds_read_b32 v82, v142 offset:1344
	ds_read_b128 v[66:69], v141 offset:1600
	ds_read_b128 v[62:65], v141 offset:1344
	ds_read_b128 v[70:73], v141 offset:1856
	ds_read_b128 v[78:81], v141 offset:2368
	v_pk_mul_f32 v[16:17], v[0:1], v[110:111]
	v_pk_mul_f32 v[20:21], v[0:1], v[100:101]
	v_pk_fma_f32 v[16:17], v[2:3], v[112:113], v[16:17]
	v_pk_fma_f32 v[20:21], v[2:3], v[102:103], v[20:21]
	v_add_f32_e32 v18, v16, v17
	v_pk_fma_f32 v[4:5], v[0:1], v[106:107], v[8:9]
	v_add_f32_e32 v200, v20, v21
	v_add_f32_dpp v18, v18, v18 quad_perm:[1,0,3,2] row_mask:0xf bank_mask:0xf bound_ctrl:1
	v_pk_fma_f32 v[6:7], v[2:3], v[108:109], v[10:11]
	s_nop 0
	v_add_f32_dpp v18, v18, v18 quad_perm:[2,3,0,1] row_mask:0xf bank_mask:0xf bound_ctrl:1
	v_add_f32_dpp v200, v200, v200 row_ror:8 row_mask:0xf bank_mask:0xc bound_ctrl:1
	v_add_f32_dpp v18, v18, v18 row_half_mirror row_mask:0xf bank_mask:0xf bound_ctrl:1
	v_add_f32_dpp v200, v190, v190 row_ror:8 row_mask:0xf bank_mask:0x3 bound_ctrl:1
	v_add_f32_dpp v18, v18, v18 row_ror:8 row_mask:0xf bank_mask:0xf bound_ctrl:1
	v_pk_fma_f32 v[0:1], v[114:115], v[18:19], v[4:5] op_sel_hi:[1,0,1] neg_lo:[1,0,0] neg_hi:[1,0,0]
	v_pk_fma_f32 v[2:3], v[116:117], v[18:19], v[6:7] op_sel_hi:[1,0,1] neg_lo:[1,0,0] neg_hi:[1,0,0]
	s_waitcnt lgkmcnt(6)
	v_pk_mul_f32 v[8:9], v[52:53], v[60:61] op_sel_hi:[1,0]
	v_pk_mul_f32 v[10:11], v[54:55], v[60:61] op_sel_hi:[1,0]
	s_add_i32 s4, s4, 1
	s_mov_b32 s0, s6
	s_mov_b32 s6, s7
	s_mov_b32 s7, s25
	s_mov_b32 s25, s0
	v_mov_b32_e32 v139, v141
	v_mov_b32_e32 v140, v142
	v_add_u32_e32 v141, s7, v24
	v_add_u32_e32 v142, s7, v25
	v_add_u32_e32 v143, s7, v26
	v_add_u32_e32 v35, s7, v27
	ds_read_b128 v[96:99], v139 offset:3456
	ds_read_b32 v104, v140 offset:2688
	ds_read_b128 v[88:91], v139 offset:2944
	ds_read_b128 v[84:87], v139 offset:2688
	ds_read_b128 v[92:95], v139 offset:3200
	ds_read_b128 v[100:103], v139 offset:3712
	v_pk_mul_f32 v[16:17], v[0:1], v[44:45]
	v_pk_mul_f32 v[20:21], v[0:1], v[122:123]
	v_pk_fma_f32 v[16:17], v[2:3], v[46:47], v[16:17]
	v_pk_fma_f32 v[20:21], v[2:3], v[124:125], v[20:21]
	v_add_f32_e32 v18, v16, v17
	v_pk_fma_f32 v[4:5], v[0:1], v[40:41], v[8:9]
	v_add_f32_e32 v201, v20, v21
	v_add_f32_dpp v18, v18, v18 quad_perm:[1,0,3,2] row_mask:0xf bank_mask:0xf bound_ctrl:1
	v_pk_fma_f32 v[6:7], v[2:3], v[42:43], v[10:11]
	s_nop 0
	v_add_f32_dpp v18, v18, v18 quad_perm:[2,3,0,1] row_mask:0xf bank_mask:0xf bound_ctrl:1
	v_add_f32_dpp v201, v201, v201 row_ror:8 row_mask:0xf bank_mask:0xc bound_ctrl:1
	v_add_f32_dpp v18, v18, v18 row_half_mirror row_mask:0xf bank_mask:0xf bound_ctrl:1
	v_add_f32_dpp v201, v191, v191 row_ror:8 row_mask:0xf bank_mask:0x3 bound_ctrl:1
	v_add_f32_dpp v18, v18, v18 row_ror:8 row_mask:0xf bank_mask:0xf bound_ctrl:1
	v_pk_fma_f32 v[0:1], v[48:49], v[18:19], v[4:5] op_sel_hi:[1,0,1] neg_lo:[1,0,0] neg_hi:[1,0,0]
	v_pk_fma_f32 v[2:3], v[50:51], v[18:19], v[6:7] op_sel_hi:[1,0,1] neg_lo:[1,0,0] neg_hi:[1,0,0]
	s_waitcnt lgkmcnt(6)
	v_pk_mul_f32 v[8:9], v[74:75], v[82:83] op_sel_hi:[1,0]
	v_pk_mul_f32 v[10:11], v[76:77], v[82:83] op_sel_hi:[1,0]
	ds_read_b128 v[118:121], v139 offset:4800
	ds_read_b32 v126, v140 offset:4032
	ds_read_b128 v[110:113], v139 offset:4288
	ds_read_b128 v[106:109], v139 offset:4032
	ds_read_b128 v[114:117], v139 offset:4544
	ds_read_b128 v[122:125], v139 offset:5056
	v_pk_mul_f32 v[16:17], v[0:1], v[66:67]
	v_pk_mul_f32 v[20:21], v[0:1], v[56:57]
	v_pk_fma_f32 v[16:17], v[2:3], v[68:69], v[16:17]
	v_pk_fma_f32 v[20:21], v[2:3], v[58:59], v[20:21]
	v_add_f32_e32 v18, v16, v17
	v_pk_fma_f32 v[4:5], v[0:1], v[62:63], v[8:9]
	v_add_f32_e32 v12, v20, v21
	v_add_f32_dpp v18, v18, v18 quad_perm:[1,0,3,2] row_mask:0xf bank_mask:0xf bound_ctrl:1
	v_pk_fma_f32 v[6:7], v[2:3], v[64:65], v[10:11]
	v_add_f32_dpp v196, v196, v196 row_half_mirror row_mask:0xf bank_mask:0xa bound_ctrl:1
	v_add_f32_dpp v18, v18, v18 quad_perm:[2,3,0,1] row_mask:0xf bank_mask:0xf bound_ctrl:1
	v_add_f32_dpp v196, v192, v192 row_half_mirror row_mask:0xf bank_mask:0x5 bound_ctrl:1
	v_add_f32_dpp v18, v18, v18 row_half_mirror row_mask:0xf bank_mask:0xf bound_ctrl:1
	v_add_f32_dpp v197, v197, v197 row_half_mirror row_mask:0xf bank_mask:0xa bound_ctrl:1
	v_add_f32_dpp v18, v18, v18 row_ror:8 row_mask:0xf bank_mask:0xf bound_ctrl:1
	v_pk_fma_f32 v[0:1], v[70:71], v[18:19], v[4:5] op_sel_hi:[1,0,1] neg_lo:[1,0,0] neg_hi:[1,0,0]
	v_pk_fma_f32 v[2:3], v[72:73], v[18:19], v[6:7] op_sel_hi:[1,0,1] neg_lo:[1,0,0] neg_hi:[1,0,0]
	s_waitcnt lgkmcnt(6)
	v_pk_mul_f32 v[8:9], v[96:97], v[104:105] op_sel_hi:[1,0]
	v_pk_mul_f32 v[10:11], v[98:99], v[104:105] op_sel_hi:[1,0]
	ds_read_b128 v[52:55], v139 offset:6144
	ds_read_b32 v60, v140 offset:5376
	ds_read_b128 v[44:47], v139 offset:5632
	ds_read_b128 v[40:43], v139 offset:5376
	ds_read_b128 v[48:51], v139 offset:5888
	ds_read_b128 v[56:59], v139 offset:6400
	v_pk_mul_f32 v[16:17], v[0:1], v[88:89]
	v_pk_mul_f32 v[20:21], v[0:1], v[78:79]
	v_pk_fma_f32 v[16:17], v[2:3], v[90:91], v[16:17]
	v_pk_fma_f32 v[20:21], v[2:3], v[80:81], v[20:21]
	v_add_f32_e32 v18, v16, v17
	v_pk_fma_f32 v[4:5], v[0:1], v[84:85], v[8:9]
	v_add_f32_e32 v13, v20, v21
	v_add_f32_dpp v18, v18, v18 quad_perm:[1,0,3,2] row_mask:0xf bank_mask:0xf bound_ctrl:1
	v_pk_fma_f32 v[6:7], v[2:3], v[86:87], v[10:11]
	v_add_f32_dpp v197, v193, v193 row_half_mirror row_mask:0xf bank_mask:0x5 bound_ctrl:1
	v_add_f32_dpp v18, v18, v18 quad_perm:[2,3,0,1] row_mask:0xf bank_mask:0xf bound_ctrl:1
	v_add_f32_dpp v200, v200, v200 row_half_mirror row_mask:0xf bank_mask:0xa bound_ctrl:1
	v_add_f32_dpp v18, v18, v18 row_half_mirror row_mask:0xf bank_mask:0xf bound_ctrl:1
	v_add_f32_dpp v200, v194, v194 row_half_mirror row_mask:0xf bank_mask:0x5 bound_ctrl:1
	v_add_f32_dpp v18, v18, v18 row_ror:8 row_mask:0xf bank_mask:0xf bound_ctrl:1
	v_pk_fma_f32 v[0:1], v[92:93], v[18:19], v[4:5] op_sel_hi:[1,0,1] neg_lo:[1,0,0] neg_hi:[1,0,0]
	v_pk_fma_f32 v[2:3], v[94:95], v[18:19], v[6:7] op_sel_hi:[1,0,1] neg_lo:[1,0,0] neg_hi:[1,0,0]
	s_waitcnt lgkmcnt(6)
	v_pk_mul_f32 v[8:9], v[118:119], v[126:127] op_sel_hi:[1,0]
	v_pk_mul_f32 v[10:11], v[120:121], v[126:127] op_sel_hi:[1,0]
	ds_read_b128 v[74:77], v139 offset:7488
	ds_read_b32 v82, v140 offset:6720
	ds_read_b128 v[66:69], v139 offset:6976
	ds_read_b128 v[62:65], v139 offset:6720
	ds_read_b128 v[70:73], v139 offset:7232
	ds_read_b128 v[78:81], v139 offset:7744
	v_pk_mul_f32 v[16:17], v[0:1], v[110:111]
	v_pk_mul_f32 v[20:21], v[0:1], v[100:101]
	v_pk_fma_f32 v[16:17], v[2:3], v[112:113], v[16:17]
	v_pk_fma_f32 v[20:21], v[2:3], v[102:103], v[20:21]
	v_add_f32_e32 v18, v16, v17
	v_pk_fma_f32 v[4:5], v[0:1], v[106:107], v[8:9]
	v_add_f32_e32 v14, v20, v21
	v_add_f32_dpp v18, v18, v18 quad_perm:[1,0,3,2] row_mask:0xf bank_mask:0xf bound_ctrl:1
	v_pk_fma_f32 v[6:7], v[2:3], v[108:109], v[10:11]
	v_add_f32_dpp v201, v201, v201 row_half_mirror row_mask:0xf bank_mask:0xa bound_ctrl:1
	v_add_f32_dpp v18, v18, v18 quad_perm:[2,3,0,1] row_mask:0xf bank_mask:0xf bound_ctrl:1
	v_add_f32_dpp v201, v195, v195 row_half_mirror row_mask:0xf bank_mask:0x5 bound_ctrl:1
	v_add_f32_dpp v18, v18, v18 row_half_mirror row_mask:0xf bank_mask:0xf bound_ctrl:1
	v_cndmask_b32_e64 v22, v196, v200, s[36:37]
	v_add_f32_dpp v18, v18, v18 row_ror:8 row_mask:0xf bank_mask:0xf bound_ctrl:1
	v_pk_fma_f32 v[0:1], v[114:115], v[18:19], v[4:5] op_sel_hi:[1,0,1] neg_lo:[1,0,0] neg_hi:[1,0,0]
	v_pk_fma_f32 v[2:3], v[116:117], v[18:19], v[6:7] op_sel_hi:[1,0,1] neg_lo:[1,0,0] neg_hi:[1,0,0]
	s_waitcnt lgkmcnt(6)
	v_pk_mul_f32 v[8:9], v[52:53], v[60:61] op_sel_hi:[1,0]
	v_pk_mul_f32 v[10:11], v[54:55], v[60:61] op_sel_hi:[1,0]
	ds_read_b128 v[96:99], v139 offset:8832
	ds_read_b32 v104, v140 offset:8064
	ds_read_b128 v[88:91], v139 offset:8320
	ds_read_b128 v[84:87], v139 offset:8064
	ds_read_b128 v[92:95], v139 offset:8576
	ds_read_b128 v[100:103], v139 offset:9088
	v_pk_mul_f32 v[16:17], v[0:1], v[44:45]
	v_pk_mul_f32 v[20:21], v[0:1], v[122:123]
	v_pk_fma_f32 v[16:17], v[2:3], v[46:47], v[16:17]
	v_pk_fma_f32 v[20:21], v[2:3], v[124:125], v[20:21]
	v_add_f32_e32 v18, v16, v17
	v_pk_fma_f32 v[4:5], v[0:1], v[40:41], v[8:9]
	v_add_f32_e32 v15, v20, v21
	v_add_f32_dpp v18, v18, v18 quad_perm:[1,0,3,2] row_mask:0xf bank_mask:0xf bound_ctrl:1
	v_pk_fma_f32 v[6:7], v[2:3], v[42:43], v[10:11]
	v_cndmask_b32_e64 v202, v200, v196, s[36:37]
	v_add_f32_dpp v18, v18, v18 quad_perm:[2,3,0,1] row_mask:0xf bank_mask:0xf bound_ctrl:1
	v_add_f32_dpp v200, v202, v22 quad_perm:[2,3,0,1] row_mask:0xf bank_mask:0xf bound_ctrl:1
	v_add_f32_dpp v18, v18, v18 row_half_mirror row_mask:0xf bank_mask:0xf bound_ctrl:1
	v_cndmask_b32_e64 v203, v197, v201, s[36:37]
	v_add_f32_dpp v18, v18, v18 row_ror:8 row_mask:0xf bank_mask:0xf bound_ctrl:1
	v_pk_fma_f32 v[0:1], v[48:49], v[18:19], v[4:5] op_sel_hi:[1,0,1] neg_lo:[1,0,0] neg_hi:[1,0,0]
	v_pk_fma_f32 v[2:3], v[50:51], v[18:19], v[6:7] op_sel_hi:[1,0,1] neg_lo:[1,0,0] neg_hi:[1,0,0]
	s_waitcnt lgkmcnt(6)
	v_pk_mul_f32 v[8:9], v[74:75], v[82:83] op_sel_hi:[1,0]
	v_pk_mul_f32 v[10:11], v[76:77], v[82:83] op_sel_hi:[1,0]
	ds_read_b128 v[118:121], v139 offset:10176
	ds_read_b32 v126, v140 offset:9408
	ds_read_b128 v[110:113], v139 offset:9664
	ds_read_b128 v[106:109], v139 offset:9408
	ds_read_b128 v[114:117], v139 offset:9920
	ds_read_b128 v[122:125], v139 offset:10432
	v_pk_mul_f32 v[16:17], v[0:1], v[66:67]
	v_pk_mul_f32 v[20:21], v[0:1], v[56:57]
	v_pk_fma_f32 v[16:17], v[2:3], v[68:69], v[16:17]
	v_pk_fma_f32 v[20:21], v[2:3], v[58:59], v[20:21]
	v_add_f32_e32 v18, v16, v17
	v_pk_fma_f32 v[4:5], v[0:1], v[62:63], v[8:9]
	v_add_f32_e32 v188, v20, v21
	v_add_f32_dpp v18, v18, v18 quad_perm:[1,0,3,2] row_mask:0xf bank_mask:0xf bound_ctrl:1
	v_pk_fma_f32 v[6:7], v[2:3], v[64:65], v[10:11]
	v_cndmask_b32_e64 v202, v201, v197, s[36:37]
	v_add_f32_dpp v18, v18, v18 quad_perm:[2,3,0,1] row_mask:0xf bank_mask:0xf bound_ctrl:1
	v_add_f32_dpp v201, v202, v203 quad_perm:[2,3,0,1] row_mask:0xf bank_mask:0xf bound_ctrl:1
	v_add_f32_dpp v18, v18, v18 row_half_mirror row_mask:0xf bank_mask:0xf bound_ctrl:1
	v_cndmask_b32_e64 v22, v200, v201, s[38:39]
	v_add_f32_dpp v18, v18, v18 row_ror:8 row_mask:0xf bank_mask:0xf bound_ctrl:1
	v_pk_fma_f32 v[0:1], v[70:71], v[18:19], v[4:5] op_sel_hi:[1,0,1] neg_lo:[1,0,0] neg_hi:[1,0,0]
	v_pk_fma_f32 v[2:3], v[72:73], v[18:19], v[6:7] op_sel_hi:[1,0,1] neg_lo:[1,0,0] neg_hi:[1,0,0]
	s_waitcnt lgkmcnt(6)
	v_pk_mul_f32 v[8:9], v[96:97], v[104:105] op_sel_hi:[1,0]
	v_pk_mul_f32 v[10:11], v[98:99], v[104:105] op_sel_hi:[1,0]
	ds_read_b128 v[52:55], v139 offset:11520
	ds_read_b32 v60, v140 offset:10752
	ds_read_b128 v[44:47], v139 offset:11008
	ds_read_b128 v[40:43], v139 offset:10752
	ds_read_b128 v[48:51], v139 offset:11264
	ds_read_b128 v[56:59], v139 offset:11776
	v_pk_mul_f32 v[16:17], v[0:1], v[88:89]
	v_pk_mul_f32 v[20:21], v[0:1], v[78:79]
	v_pk_fma_f32 v[16:17], v[2:3], v[90:91], v[16:17]
	v_pk_fma_f32 v[20:21], v[2:3], v[80:81], v[20:21]
	v_add_f32_e32 v18, v16, v17
	v_pk_fma_f32 v[4:5], v[0:1], v[84:85], v[8:9]
	v_add_f32_e32 v189, v20, v21
	v_add_f32_dpp v18, v18, v18 quad_perm:[1,0,3,2] row_mask:0xf bank_mask:0xf bound_ctrl:1
	v_pk_fma_f32 v[6:7], v[2:3], v[86:87], v[10:11]
	v_cndmask_b32_e64 v202, v201, v200, s[38:39]
	v_add_f32_dpp v18, v18, v18 quad_perm:[2,3,0,1] row_mask:0xf bank_mask:0xf bound_ctrl:1
	v_add_f32_dpp v23, v202, v22 quad_perm:[1,0,3,2] row_mask:0xf bank_mask:0xf bound_ctrl:1
	v_add_f32_dpp v18, v18, v18 row_half_mirror row_mask:0xf bank_mask:0xf bound_ctrl:1
	s_nop 0
	v_add_f32_dpp v18, v18, v18 row_ror:8 row_mask:0xf bank_mask:0xf bound_ctrl:1
	v_pk_fma_f32 v[0:1], v[92:93], v[18:19], v[4:5] op_sel_hi:[1,0,1] neg_lo:[1,0,0] neg_hi:[1,0,0]
	v_pk_fma_f32 v[2:3], v[94:95], v[18:19], v[6:7] op_sel_hi:[1,0,1] neg_lo:[1,0,0] neg_hi:[1,0,0]
	s_waitcnt lgkmcnt(6)
	v_pk_mul_f32 v[8:9], v[118:119], v[126:127] op_sel_hi:[1,0]
	v_pk_mul_f32 v[10:11], v[120:121], v[126:127] op_sel_hi:[1,0]
	s_cmp_eq_u32 s4, 0
	s_cbranch_scc1 .Lscan_noy1
	global_store_dword v138, v23, s[96:97]
	v_add_u32_e32 v138, s90, v138

.Lscan_wd_1:
	ds_write_b128 v143, v[168:171]
	ds_write_b128 v143, v[172:175] offset:256
	ds_write_b128 v143, v[176:179] offset:512
	ds_write_b128 v143, v[180:183] offset:768
	ds_write_b128 v143, v[184:187] offset:1024
	ds_write_b32 v35, v167
	ds_read_b128 v[74:77], v139 offset:18240
	ds_read_b32 v82, v140 offset:17472
	ds_read_b128 v[66:69], v139 offset:17728
	ds_read_b128 v[62:65], v139 offset:17472
	ds_read_b128 v[70:73], v139 offset:17984
	ds_read_b128 v[78:81], v139 offset:18496
	v_pk_mul_f32 v[16:17], v[0:1], v[110:111]
	v_pk_mul_f32 v[20:21], v[0:1], v[100:101]
	v_pk_fma_f32 v[16:17], v[2:3], v[112:113], v[16:17]
	v_pk_fma_f32 v[20:21], v[2:3], v[102:103], v[20:21]
	v_add_f32_e32 v18, v16, v17
	v_pk_fma_f32 v[4:5], v[0:1], v[106:107], v[8:9]
	v_add_f32_e32 v194, v20, v21
	v_add_f32_dpp v18, v18, v18 quad_perm:[1,0,3,2] row_mask:0xf bank_mask:0xf bound_ctrl:1
	v_pk_fma_f32 v[6:7], v[2:3], v[108:109], v[10:11]
	s_nop 0
	v_add_f32_dpp v18, v18, v18 quad_perm:[2,3,0,1] row_mask:0xf bank_mask:0xf bound_ctrl:1
	v_add_f32_dpp v194, v194, v194 row_ror:8 row_mask:0xf bank_mask:0xc bound_ctrl:1
	v_add_f32_dpp v18, v18, v18 row_half_mirror row_mask:0xf bank_mask:0xf bound_ctrl:1
	v_add_f32_dpp v194, v14, v14 row_ror:8 row_mask:0xf bank_mask:0x3 bound_ctrl:1
	v_add_f32_dpp v18, v18, v18 row_ror:8 row_mask:0xf bank_mask:0xf bound_ctrl:1
	v_pk_fma_f32 v[0:1], v[114:115], v[18:19], v[4:5] op_sel_hi:[1,0,1] neg_lo:[1,0,0] neg_hi:[1,0,0]
	v_pk_fma_f32 v[2:3], v[116:117], v[18:19], v[6:7] op_sel_hi:[1,0,1] neg_lo:[1,0,0] neg_hi:[1,0,0]
	s_waitcnt lgkmcnt(6)
	v_pk_mul_f32 v[8:9], v[52:53], v[60:61] op_sel_hi:[1,0]
	v_pk_mul_f32 v[10:11], v[54:55], v[60:61] op_sel_hi:[1,0]
	ds_read_b128 v[96:99], v139 offset:19584
	ds_read_b32 v104, v140 offset:18816
	ds_read_b128 v[88:91], v139 offset:19072
	ds_read_b128 v[84:87], v139 offset:18816
	ds_read_b128 v[92:95], v139 offset:19328
	ds_read_b128 v[100:103], v139 offset:19840
	v_pk_mul_f32 v[16:17], v[0:1], v[44:45]
	v_pk_mul_f32 v[20:21], v[0:1], v[122:123]
	v_pk_fma_f32 v[16:17], v[2:3], v[46:47], v[16:17]
	v_pk_fma_f32 v[20:21], v[2:3], v[124:125], v[20:21]
	v_add_f32_e32 v18, v16, v17
	v_pk_fma_f32 v[4:5], v[0:1], v[40:41], v[8:9]
	v_add_f32_e32 v195, v20, v21
	v_add_f32_dpp v18, v18, v18 quad_perm:[1,0,3,2] row_mask:0xf bank_mask:0xf bound_ctrl:1
	v_pk_fma_f32 v[6:7], v[2:3], v[42:43], v[10:11]
	s_nop 0
	v_add_f32_dpp v18, v18, v18 quad_perm:[2,3,0,1] row_mask:0xf bank_mask:0xf bound_ctrl:1
	v_add_f32_dpp v195, v195, v195 row_ror:8 row_mask:0xf bank_mask:0xc bound_ctrl:1
	v_add_f32_dpp v18, v18, v18 row_half_mirror row_mask:0xf bank_mask:0xf bound_ctrl:1
	v_add_f32_dpp v195, v15, v15 row_ror:8 row_mask:0xf bank_mask:0x3 bound_ctrl:1
	v_add_f32_dpp v18, v18, v18 row_ror:8 row_mask:0xf bank_mask:0xf bound_ctrl:1
	v_pk_fma_f32 v[0:1], v[48:49], v[18:19], v[4:5] op_sel_hi:[1,0,1] neg_lo:[1,0,0] neg_hi:[1,0,0]
	v_pk_fma_f32 v[2:3], v[50:51], v[18:19], v[6:7] op_sel_hi:[1,0,1] neg_lo:[1,0,0] neg_hi:[1,0,0]
	s_waitcnt lgkmcnt(6)
	s_barrier
	s_add_i32 s0, s4, 3
	s_cmp_lt_u32 s0, s5
	s_cbranch_scc0 .Lscan_nold1
	s_mul_i32 s92, s0, s90
	v_add_u32_e32 v132, s92, v28
	v_add_u32_e32 v133, s92, v29
	v_add_u32_e32 v134, s92, v30
	v_add_u32_e32 v135, s92, v31
	v_add_u32_e32 v136, s92, v32
	v_add_u32_e32 v137, s92, v33
	global_load_dwordx4 v[168:171], v132, s[96:97]
	global_load_dwordx4 v[172:175], v133, s[96:97]
	global_load_dwordx4 v[176:179], v134, s[96:97]
	global_load_dwordx4 v[180:183], v135, s[96:97]
	global_load_dwordx4 v[184:187], v136, s[96:97]
	global_load_dword v167, v137, s[96:97]
.Lscan_nold1:
	v_pk_mul_f32 v[8:9], v[74:75], v[82:83] op_sel_hi:[1,0]
	v_pk_mul_f32 v[10:11], v[76:77], v[82:83] op_sel_hi:[1,0]
	ds_read_b128 v[118:121], v139 offset:20928
	ds_read_b32 v126, v140 offset:20160
	ds_read_b128 v[110:113], v139 offset:20416
	ds_read_b128 v[106:109], v139 offset:20160
	ds_read_b128 v[114:117], v139 offset:20672
	ds_read_b128 v[122:125], v139 offset:21184
	v_pk_mul_f32 v[16:17], v[0:1], v[66:67]
	v_pk_mul_f32 v[20:21], v[0:1], v[56:57]
	v_pk_fma_f32 v[16:17], v[2:3], v[68:69], v[16:17]
	v_pk_fma_f32 v[20:21], v[2:3], v[58:59], v[20:21]
	v_add_f32_e32 v18, v16, v17
	v_pk_fma_f32 v[4:5], v[0:1], v[62:63], v[8:9]
	v_add_f32_e32 v196, v20, v21
	v_add_f32_dpp v18, v18, v18 quad_perm:[1,0,3,2] row_mask:0xf bank_mask:0xf bound_ctrl:1
	v_pk_fma_f32 v[6:7], v[2:3], v[64:65], v[10:11]
	s_nop 0
	v_add_f32_dpp v18, v18, v18 quad_perm:[2,3,0,1] row_mask:0xf bank_mask:0xf bound_ctrl:1
	v_add_f32_dpp v196, v196, v196 row_ror:8 row_mask:0xf bank_mask:0xc bound_ctrl:1
	v_add_f32_dpp v18, v18, v18 row_half_mirror row_mask:0xf bank_mask:0xf bound_ctrl:1
	v_add_f32_dpp v196, v188, v188 row_ror:8 row_mask:0xf bank_mask:0x3 bound_ctrl:1
	v_add_f32_dpp v18, v18, v18 row_ror:8 row_mask:0xf bank_mask:0xf bound_ctrl:1
	v_pk_fma_f32 v[0:1], v[70:71], v[18:19], v[4:5] op_sel_hi:[1,0,1] neg_lo:[1,0,0] neg_hi:[1,0,0]
	v_pk_fma_f32 v[2:3], v[72:73], v[18:19], v[6:7] op_sel_hi:[1,0,1] neg_lo:[1,0,0] neg_hi:[1,0,0]
	s_waitcnt lgkmcnt(6)
	v_pk_mul_f32 v[8:9], v[96:97], v[104:105] op_sel_hi:[1,0]
	v_pk_mul_f32 v[10:11], v[98:99], v[104:105] op_sel_hi:[1,0]
	ds_read_b128 v[52:55], v141 offset:768
	ds_read_b32 v60, v142 offset:0
	ds_read_b128 v[44:47], v141 offset:256
	ds_read_b128 v[40:43], v141 offset:0
	ds_read_b128 v[48:51], v141 offset:512
	ds_read_b128 v[56:59], v141 offset:1024
	v_pk_mul_f32 v[16:17], v[0:1], v[88:89]
	v_pk_mul_f32 v[20:21], v[0:1], v[78:79]
	v_pk_fma_f32 v[16:17], v[2:3], v[90:91], v[16:17]
	v_pk_fma_f32 v[20:21], v[2:3], v[80:81], v[20:21]
	v_add_f32_e32 v18, v16, v17
	v_pk_fma_f32 v[4:5], v[0:1], v[84:85], v[8:9]
	v_add_f32_e32 v197, v20, v21
	v_add_f32_dpp v18, v18, v18 quad_perm:[1,0,3,2] row_mask:0xf bank_mask:0xf bound_ctrl:1
	v_pk_fma_f32 v[6:7], v[2:3], v[86:87], v[10:11]
	s_nop 0
	v_add_f32_dpp v18, v18, v18 quad_perm:[2,3,0,1] row_mask:0xf bank_mask:0xf bound_ctrl:1
	v_add_f32_dpp v197, v197, v197 row_ror:8 row_mask:0xf bank_mask:0xc bound_ctrl:1
	v_add_f32_dpp v18, v18, v18 row_half_mirror row_mask:0xf bank_mask:0xf bound_ctrl:1
	v_add_f32_dpp v197, v189, v189 row_ror:8 row_mask:0xf bank_mask:0x3 bound_ctrl:1
	v_add_f32_dpp v18, v18, v18 row_ror:8 row_mask:0xf bank_mask:0xf bound_ctrl:1
	v_pk_fma_f32 v[0:1], v[92:93], v[18:19], v[4:5] op_sel_hi:[1,0,1] neg_lo:[1,0,0] neg_hi:[1,0,0]
	v_pk_fma_f32 v[2:3], v[94:95], v[18:19], v[6:7] op_sel_hi:[1,0,1] neg_lo:[1,0,0] neg_hi:[1,0,0]
	s_waitcnt lgkmcnt(6)
	v_pk_mul_f32 v[8:9], v[118:119], v[126:127] op_sel_hi:[1,0]
	v_pk_mul_f32 v[10:11], v[120:121], v[126:127] op_sel_hi:[1,0]
	ds_read_b128 v[74:77], v141 offset:2112
	ds_read_b32 v82, v142 offset:1344
	ds_read_b128 v[66:69], v141 offset:1600
	ds_read_b128 v[62:65], v141 offset:1344
	ds_read_b128 v[70:73], v141 offset:1856
	ds_read_b128 v[78:81], v141 offset:2368
	v_pk_mul_f32 v[16:17], v[0:1], v[110:111]
	v_pk_mul_f32 v[20:21], v[0:1], v[100:101]
	v_pk_fma_f32 v[16:17], v[2:3], v[112:113], v[16:17]
	v_pk_fma_f32 v[20:21], v[2:3], v[102:103], v[20:21]
	v_add_f32_e32 v18, v16, v17
	v_pk_fma_f32 v[4:5], v[0:1], v[106:107], v[8:9]
	v_add_f32_e32 v200, v20, v21
	v_add_f32_dpp v18, v18, v18 quad_perm:[1,0,3,2] row_mask:0xf bank_mask:0xf bound_ctrl:1
	v_pk_fma_f32 v[6:7], v[2:3], v[108:109], v[10:11]
	s_nop 0
	v_add_f32_dpp v18, v18, v18 quad_perm:[2,3,0,1] row_mask:0xf bank_mask:0xf bound_ctrl:1
	v_add_f32_dpp v200, v200, v200 row_ror:8 row_mask:0xf bank_mask:0xc bound_ctrl:1
	v_add_f32_dpp v18, v18, v18 row_half_mirror row_mask:0xf bank_mask:0xf bound_ctrl:1
	v_add_f32_dpp v200, v190, v190 row_ror:8 row_mask:0xf bank_mask:0x3 bound_ctrl:1
	v_add_f32_dpp v18, v18, v18 row_ror:8 row_mask:0xf bank_mask:0xf bound_ctrl:1
	v_pk_fma_f32 v[0:1], v[114:115], v[18:19], v[4:5] op_sel_hi:[1,0,1] neg_lo:[1,0,0] neg_hi:[1,0,0]
	v_pk_fma_f32 v[2:3], v[116:117], v[18:19], v[6:7] op_sel_hi:[1,0,1] neg_lo:[1,0,0] neg_hi:[1,0,0]
	s_waitcnt lgkmcnt(6)
	v_pk_mul_f32 v[8:9], v[52:53], v[60:61] op_sel_hi:[1,0]
	v_pk_mul_f32 v[10:11], v[54:55], v[60:61] op_sel_hi:[1,0]
	s_add_i32 s4, s4, 1
	s_mov_b32 s0, s6
	s_mov_b32 s6, s7
	s_mov_b32 s7, s25
	s_mov_b32 s25, s0
	v_mov_b32_e32 v139, v141
	v_mov_b32_e32 v140, v142
	v_add_u32_e32 v141, s7, v24
	v_add_u32_e32 v142, s7, v25
	v_add_u32_e32 v143, s7, v26
	v_add_u32_e32 v35, s7, v27
	s_cmp_lt_u32 s4, s5
	s_cbranch_scc1 .Lscan_chunk
	v_mul_f32_e32 v201, v0, v122
	v_fmac_f32_e32 v201, v1, v123
	v_fmac_f32_e32 v201, v2, v124
	v_fmac_f32_e32 v201, v3, v125
	s_nop 1
	v_add_f32_dpp v201, v201, v201 row_ror:8 row_mask:0xf bank_mask:0xc bound_ctrl:1
	v_add_f32_dpp v201, v191, v191 row_ror:8 row_mask:0xf bank_mask:0x3 bound_ctrl:1
	s_nop 1
	v_add_f32_dpp v196, v196, v196 row_half_mirror row_mask:0xf bank_mask:0xa bound_ctrl:1
	v_add_f32_dpp v196, v192, v192 row_half_mirror row_mask:0xf bank_mask:0x5 bound_ctrl:1
	v_add_f32_dpp v197, v197, v197 row_half_mirror row_mask:0xf bank_mask:0xa bound_ctrl:1
	v_add_f32_dpp v197, v193, v193 row_half_mirror row_mask:0xf bank_mask:0x5 bound_ctrl:1
	v_add_f32_dpp v200, v200, v200 row_half_mirror row_mask:0xf bank_mask:0xa bound_ctrl:1
	v_add_f32_dpp v200, v194, v194 row_half_mirror row_mask:0xf bank_mask:0x5 bound_ctrl:1
	v_add_f32_dpp v201, v201, v201 row_half_mirror row_mask:0xf bank_mask:0xa bound_ctrl:1
	v_add_f32_dpp v201, v195, v195 row_half_mirror row_mask:0xf bank_mask:0x5 bound_ctrl:1
	s_nop 1
	v_cndmask_b32_e64 v22, v196, v200, s[36:37]
	v_cndmask_b32_e64 v202, v200, v196, s[36:37]
	s_nop 1
	v_add_f32_dpp v200, v202, v22 quad_perm:[2,3,0,1] row_mask:0xf bank_mask:0xf bound_ctrl:1
	v_cndmask_b32_e64 v203, v197, v201, s[36:37]
	v_cndmask_b32_e64 v202, v201, v197, s[36:37]
	s_nop 1
	v_add_f32_dpp v201, v202, v203 quad_perm:[2,3,0,1] row_mask:0xf bank_mask:0xf bound_ctrl:1
	v_cndmask_b32_e64 v22, v200, v201, s[38:39]
	v_cndmask_b32_e64 v202, v201, v200, s[38:39]
	s_nop 1
	v_add_f32_dpp v23, v202, v22 quad_perm:[1,0,3,2] row_mask:0xf bank_mask:0xf bound_ctrl:1
	global_store_dword v138, v23, s[96:97]
	s_cmp_eq_u32 s28, 0
	s_cbranch_scc1 .Lscan_done
	v_readlane_b32 s0, v254, 57
	v_readlane_b32 s1, v254, 58
	s_nop 4
	global_store_dwordx4 v39, v[0:3], s[0:1]
